# STEP2 and ctx-DFT residual epilogues: issue a row-group's read-modify-write loads together (counted waits) instead of load-wait-store per element
# speedup vs baseline: 1.0166x; 1.0089x over previous
; #define PG8_STAGE(bufoff, gbase, voff) do { _Pragma("unroll") for (int _i = 0; _i < 2; ++_i) \
;         __builtin_amdgcn_global_load_lds((const unsigned*)((const char*)(gbase) + (voff)[_i]), (LAS unsigned*)(lds + (bufoff) + ldsw + _i * 8192), 16, 0, 0); } while (0)
; #define PG8_WAIT_V(n) asm volatile("s_waitcnt vmcnt(" #n ")" ::: "memory")
; #define PG8_BAR __builtin_amdgcn_s_barrier()
; template <class Epi, class Sched>
; __device__ __forceinline__ void gemm_phase(LAS unsigned char* lds, const int K, const int lda, const int ldb, const Sched& S, const Epi& E) {
;     ...
;         for (int t = 0; t < nt; t += 2) {
;             const bool last = (t == nt - 2);
;             const char* a1 = cA + (size_t)(t + 1) * kstep;
;             const char* a2 = last ? nA : cA + (size_t)(t + 2) * kstep; const char* b2 = last ? nB : cB + (size_t)(t + 2) * kstep;
;             const char* a3 = a2 + kstep; const char* b3 = b2 + kstep;
;             PG8_LDB(B0, 0, 0); PG8_SCHED; PG8_LDA(At, 0, 0); PG8_STAGE_A(PG8_SA(1, 1), a1, 1, vcur);
;             if constexpr (GATHER) { if (last) {
; #pragma unroll
;                 for (int h = 0; h < 2; ++h)
; #pragma unroll
;                     for (int i = 0; i < 2; ++i) vcur[h][i] = vnxt[h][i]; } }
;             PG8_WAIT_L(8); PG8_BAR; PG8_WAIT_L(0); PG8_MMA(0, 0, At, B0); PG8_BAR; PG8_SCHED;
;             PG8_LDB(B1, 0, 1); PG8_STAGE(PG8_SB(0, 0), b2, voffB);
;             PG8_BAR; PG8_WAIT_L(0); PG8_MMA(0, 1, At, B1); PG8_BAR;
;             PG8_LDA(At, 0, 1); PG8_STAGE_A(PG8_SA(0, 0), a2, 0, vcur);
;             PG8_BAR; PG8_WAIT_L(0); PG8_MMA(1, 0, At, B0); PG8_BAR; PG8_SCHED;
;             PG8_STAGE(PG8_SB(0, 1), b2 + hstepB, voffB);
;             PG8_WAIT_V(6); PG8_BAR; PG8_MMA(1, 1, At, B1); PG8_BAR;
;             PG8_LDB(B0, 1, 0); PG8_SCHED; PG8_LDA(At, 1, 0); PG8_STAGE_A(PG8_SA(0, 1), a2, 1, vcur);
;             PG8_WAIT_L(8); PG8_BAR; PG8_WAIT_L(0); PG8_MMA(0, 0, At, B0); PG8_BAR; PG8_SCHED;
;             PG8_LDB(B1, 1, 1); PG8_STAGE(PG8_SB(1, 0), b3, voffB);
;             PG8_BAR; PG8_WAIT_L(0); PG8_MMA(0, 1, At, B1); PG8_BAR;
;             PG8_LDA(At, 1, 1); PG8_STAGE_A(PG8_SA(1, 0), a3, 0, vcur);
;             PG8_BAR; PG8_WAIT_L(0); PG8_MMA(1, 0, At, B0); PG8_BAR; PG8_SCHED;
;             PG8_STAGE(PG8_SB(1, 1), b3 + hstepB, voffB);
;             PG8_WAIT_V(6); PG8_BAR; PG8_MMA(1, 1, At, B1); PG8_BAR;
.LBB0_270:
	s_add_u32 s2, s10, 0xfffe0080
	s_addc_u32 s3, s11, -1
	s_add_i32 s20, 0, 0x10000
	v_add_u32_e32 v163, s20, v160
	ds_read_b128 v[152:155], v163
	ds_read_b128 v[156:159], v163 offset:1024
	ds_read_b128 v[164:167], v163 offset:2048
	ds_read_b128 v[168:171], v163 offset:3072
	s_cmp_eq_u32 s43, 4
	s_cselect_b32 s15, s7, s3
	s_cselect_b32 s14, s6, s2
	s_cselect_b32 s13, s9, s42
	s_cselect_b32 s12, s8, s41
	v_lshl_add_u64 v[214:215], s[10:11], 0, v[148:149]
	s_add_i32 m0, s19, 0xc000
	ds_read_b128 v[172:175], v162
	ds_read_b128 v[176:179], v162 offset:1024
	ds_read_b128 v[180:183], v162 offset:2048
	ds_read_b128 v[184:187], v162 offset:3072
	ds_read_b128 v[188:191], v162 offset:4096
	ds_read_b128 v[192:195], v162 offset:5120
	ds_read_b128 v[216:219], v162 offset:6144
	ds_read_b128 v[220:223], v162 offset:7168
	global_load_lds_dwordx4 v[214:215], off
	v_lshl_add_u64 v[214:215], s[10:11], 0, v[150:151]
	s_add_i32 m0, s19, 0xe000
	s_nop 0
	global_load_lds_dwordx4 v[214:215], off
	s_waitcnt lgkmcnt(8)
	s_barrier
	s_waitcnt lgkmcnt(0)
	s_setprio 1
	s_waitcnt lgkmcnt(0)
	v_mfma_f32_16x16x32_bf16 v[126:129], v[152:155], v[172:175], v[126:129]
	v_mfma_f32_16x16x32_bf16 v[98:101], v[164:167], v[172:175], v[98:101]
	v_mfma_f32_16x16x32_bf16 v[122:125], v[152:155], v[180:183], v[122:125]
	v_mfma_f32_16x16x32_bf16 v[90:93], v[164:167], v[180:183], v[90:93]
	v_mfma_f32_16x16x32_bf16 v[118:121], v[152:155], v[188:191], v[118:121]
	v_mfma_f32_16x16x32_bf16 v[86:89], v[164:167], v[188:191], v[86:89]
	v_mfma_f32_16x16x32_bf16 v[114:117], v[152:155], v[216:219], v[114:117]
	v_mfma_f32_16x16x32_bf16 v[82:85], v[164:167], v[216:219], v[82:85]
	v_mfma_f32_16x16x32_bf16 v[126:129], v[156:159], v[176:179], v[126:129]
	v_mfma_f32_16x16x32_bf16 v[98:101], v[168:171], v[176:179], v[98:101]
	v_mfma_f32_16x16x32_bf16 v[122:125], v[156:159], v[184:187], v[122:125]
	v_mfma_f32_16x16x32_bf16 v[90:93], v[168:171], v[184:187], v[90:93]
	v_mfma_f32_16x16x32_bf16 v[118:121], v[156:159], v[192:195], v[118:121]
	v_mfma_f32_16x16x32_bf16 v[86:89], v[168:171], v[192:195], v[86:89]
	v_mfma_f32_16x16x32_bf16 v[114:117], v[156:159], v[220:223], v[114:117]
	v_mfma_f32_16x16x32_bf16 v[82:85], v[168:171], v[220:223], v[82:85]
	s_setprio 0
	s_barrier
	s_add_i32 s2, 0, 0x14000
	s_add_i32 s3, s20, s18
	v_add_u32_e32 v163, s2, v160
	v_lshl_add_u64 v[214:215], s[12:13], 0, v[0:1]
	s_mov_b32 m0, s3
	ds_read_b128 v[224:227], v163
	ds_read_b128 v[228:231], v163 offset:1024
	ds_read_b128 v[232:235], v163 offset:2048
	ds_read_b128 v[236:239], v163 offset:3072
	global_load_lds_dwordx4 v[214:215], off
	v_lshl_add_u64 v[240:241], s[12:13], 0, v[130:131]
	s_add_i32 m0, s3, 0x2000
	s_nop 0
	global_load_lds_dwordx4 v[240:241], off
	s_barrier
	s_waitcnt lgkmcnt(0)
	s_setprio 1
	s_waitcnt lgkmcnt(0)
	v_mfma_f32_16x16x32_bf16 v[66:69], v[224:227], v[172:175], v[66:69]
	v_mfma_f32_16x16x32_bf16 v[34:37], v[232:235], v[172:175], v[34:37]
	v_mfma_f32_16x16x32_bf16 v[58:61], v[224:227], v[180:183], v[58:61]
	v_mfma_f32_16x16x32_bf16 v[26:29], v[232:235], v[180:183], v[26:29]
	v_mfma_f32_16x16x32_bf16 v[54:57], v[224:227], v[188:191], v[54:57]
	v_mfma_f32_16x16x32_bf16 v[22:25], v[232:235], v[188:191], v[22:25]
	v_mfma_f32_16x16x32_bf16 v[50:53], v[224:227], v[216:219], v[50:53]
	v_mfma_f32_16x16x32_bf16 v[18:21], v[232:235], v[216:219], v[18:21]
	v_mfma_f32_16x16x32_bf16 v[66:69], v[228:231], v[176:179], v[66:69]
	v_mfma_f32_16x16x32_bf16 v[34:37], v[236:239], v[176:179], v[34:37]
	v_mfma_f32_16x16x32_bf16 v[58:61], v[228:231], v[184:187], v[58:61]
	v_mfma_f32_16x16x32_bf16 v[26:29], v[236:239], v[184:187], v[26:29]
	v_mfma_f32_16x16x32_bf16 v[54:57], v[228:231], v[192:195], v[54:57]
	v_mfma_f32_16x16x32_bf16 v[22:25], v[236:239], v[192:195], v[22:25]
	v_mfma_f32_16x16x32_bf16 v[50:53], v[228:231], v[220:223], v[50:53]
	v_mfma_f32_16x16x32_bf16 v[18:21], v[236:239], v[220:223], v[18:21]
	s_setprio 0
	s_mov_b32 m0, s19
	v_lshl_add_u64 v[242:243], s[14:15], 0, v[0:1]
	s_barrier
	ds_read_b128 v[172:175], v162 offset:16384
	ds_read_b128 v[176:179], v162 offset:17408
	ds_read_b128 v[180:183], v162 offset:18432
	ds_read_b128 v[184:187], v162 offset:19456
	ds_read_b128 v[188:191], v162 offset:20480
	ds_read_b128 v[192:195], v162 offset:21504
	ds_read_b128 v[216:219], v162 offset:22528
	ds_read_b128 v[220:223], v162 offset:23552
	global_load_lds_dwordx4 v[242:243], off
	v_lshl_add_u64 v[244:245], s[14:15], 0, v[130:131]
	s_mov_b32 m0, s30
	s_nop 0
	global_load_lds_dwordx4 v[244:245], off
	s_barrier
	s_waitcnt lgkmcnt(0)
	s_setprio 1
	s_waitcnt lgkmcnt(0)
	v_mfma_f32_16x16x32_bf16 v[110:113], v[152:155], v[172:175], v[110:113]
	v_mfma_f32_16x16x32_bf16 v[78:81], v[164:167], v[172:175], v[78:81]
	v_mfma_f32_16x16x32_bf16 v[106:109], v[152:155], v[180:183], v[106:109]
	v_mfma_f32_16x16x32_bf16 v[74:77], v[164:167], v[180:183], v[74:77]
	v_mfma_f32_16x16x32_bf16 v[102:105], v[152:155], v[188:191], v[102:105]
	v_mfma_f32_16x16x32_bf16 v[70:73], v[164:167], v[188:191], v[70:73]
	v_mfma_f32_16x16x32_bf16 v[94:97], v[152:155], v[216:219], v[94:97]
	v_mfma_f32_16x16x32_bf16 v[62:65], v[164:167], v[216:219], v[62:65]
	v_mfma_f32_16x16x32_bf16 v[110:113], v[156:159], v[176:179], v[110:113]
	v_mfma_f32_16x16x32_bf16 v[78:81], v[168:171], v[176:179], v[78:81]
	v_mfma_f32_16x16x32_bf16 v[106:109], v[156:159], v[184:187], v[106:109]
	v_mfma_f32_16x16x32_bf16 v[74:77], v[168:171], v[184:187], v[74:77]
	v_mfma_f32_16x16x32_bf16 v[102:105], v[156:159], v[192:195], v[102:105]
	v_mfma_f32_16x16x32_bf16 v[70:73], v[168:171], v[192:195], v[70:73]
	v_mfma_f32_16x16x32_bf16 v[94:97], v[156:159], v[220:223], v[94:97]
	v_mfma_f32_16x16x32_bf16 v[62:65], v[168:171], v[220:223], v[62:65]
	s_setprio 0
	s_barrier
; #define PG8_STAGE(bufoff, gbase, voff) do { _Pragma("unroll") for (int _i = 0; _i < 2; ++_i) \
;         __builtin_amdgcn_global_load_lds((const unsigned*)((const char*)(gbase) + (voff)[_i]), (LAS unsigned*)(lds + (bufoff) + ldsw + _i * 8192), 16, 0, 0); } while (0)
; #define PG8_WAIT_V(n) asm volatile("s_waitcnt vmcnt(" #n ")" ::: "memory")
; #define PG8_BAR __builtin_amdgcn_s_barrier()
; template <class Epi, class Sched>
; __device__ __forceinline__ void gemm_phase(LAS unsigned char* lds, const int K, const int lda, const int ldb, const Sched& S, const Epi& E) {
;     ...
;         for (int t = 0; t < nt; t += 2) {
;             const bool last = (t == nt - 2);
;             const char* a1 = cA + (size_t)(t + 1) * kstep;
;             const char* a2 = last ? nA : cA + (size_t)(t + 2) * kstep; const char* b2 = last ? nB : cB + (size_t)(t + 2) * kstep;
;             const char* a3 = a2 + kstep; const char* b3 = b2 + kstep;
;             PG8_LDB(B0, 0, 0); PG8_SCHED; PG8_LDA(At, 0, 0); PG8_STAGE_A(PG8_SA(1, 1), a1, 1, vcur);
;             if constexpr (GATHER) { if (last) {
; #pragma unroll
;                 for (int h = 0; h < 2; ++h)
; #pragma unroll
;                     for (int i = 0; i < 2; ++i) vcur[h][i] = vnxt[h][i]; } }
;             PG8_WAIT_L(8); PG8_BAR; PG8_WAIT_L(0); PG8_MMA(0, 0, At, B0); PG8_BAR; PG8_SCHED;
;             PG8_LDB(B1, 0, 1); PG8_STAGE(PG8_SB(0, 0), b2, voffB);
;             PG8_BAR; PG8_WAIT_L(0); PG8_MMA(0, 1, At, B1); PG8_BAR;
;             PG8_LDA(At, 0, 1); PG8_STAGE_A(PG8_SA(0, 0), a2, 0, vcur);
;             PG8_BAR; PG8_WAIT_L(0); PG8_MMA(1, 0, At, B0); PG8_BAR; PG8_SCHED;
;             PG8_STAGE(PG8_SB(0, 1), b2 + hstepB, voffB);
;             PG8_WAIT_V(6); PG8_BAR; PG8_MMA(1, 1, At, B1); PG8_BAR;
;             PG8_LDB(B0, 1, 0); PG8_SCHED; PG8_LDA(At, 1, 0); PG8_STAGE_A(PG8_SA(0, 1), a2, 1, vcur);
;             PG8_WAIT_L(8); PG8_BAR; PG8_WAIT_L(0); PG8_MMA(0, 0, At, B0); PG8_BAR; PG8_SCHED;
;             PG8_LDB(B1, 1, 1); PG8_STAGE(PG8_SB(1, 0), b3, voffB);
;             PG8_BAR; PG8_WAIT_L(0); PG8_MMA(0, 1, At, B1); PG8_BAR;
;             PG8_LDA(At, 1, 1); PG8_STAGE_A(PG8_SA(1, 0), a3, 0, vcur);
;             PG8_BAR; PG8_WAIT_L(0); PG8_MMA(1, 0, At, B0); PG8_BAR; PG8_SCHED;
;             PG8_STAGE(PG8_SB(1, 1), b3 + hstepB, voffB);
;             PG8_WAIT_V(6); PG8_BAR; PG8_MMA(1, 1, At, B1); PG8_BAR;
	s_add_u32 s44, s12, 0x20000
	s_addc_u32 s45, s13, 0
	s_add_i32 s2, s2, s18
	v_lshl_add_u64 v[152:153], s[44:45], 0, v[0:1]
	s_mov_b32 m0, s2
	s_nop 0
	global_load_lds_dwordx4 v[152:153], off
	v_lshl_add_u64 v[152:153], s[44:45], 0, v[130:131]
	s_add_i32 m0, s2, 0x2000
	s_nop 0
	global_load_lds_dwordx4 v[152:153], off
	s_waitcnt vmcnt(6)
	s_barrier
	s_setprio 1
	v_mfma_f32_16x16x32_bf16 v[46:49], v[224:227], v[172:175], v[46:49]
	v_mfma_f32_16x16x32_bf16 v[14:17], v[232:235], v[172:175], v[14:17]
	v_mfma_f32_16x16x32_bf16 v[42:45], v[224:227], v[180:183], v[42:45]
	v_mfma_f32_16x16x32_bf16 v[10:13], v[232:235], v[180:183], v[10:13]
	v_mfma_f32_16x16x32_bf16 v[38:41], v[224:227], v[188:191], v[38:41]
	v_mfma_f32_16x16x32_bf16 v[6:9], v[232:235], v[188:191], v[6:9]
	v_mfma_f32_16x16x32_bf16 v[30:33], v[224:227], v[216:219], v[30:33]
	v_mfma_f32_16x16x32_bf16 v[2:5], v[232:235], v[216:219], v[2:5]
	v_mfma_f32_16x16x32_bf16 v[46:49], v[228:231], v[176:179], v[46:49]
	v_mfma_f32_16x16x32_bf16 v[14:17], v[236:239], v[176:179], v[14:17]
	v_mfma_f32_16x16x32_bf16 v[42:45], v[228:231], v[184:187], v[42:45]
	v_mfma_f32_16x16x32_bf16 v[10:13], v[236:239], v[184:187], v[10:13]
	v_mfma_f32_16x16x32_bf16 v[38:41], v[228:231], v[192:195], v[38:41]
	v_mfma_f32_16x16x32_bf16 v[6:9], v[236:239], v[192:195], v[6:9]
	v_mfma_f32_16x16x32_bf16 v[30:33], v[228:231], v[220:223], v[30:33]
	v_mfma_f32_16x16x32_bf16 v[2:5], v[236:239], v[220:223], v[2:5]
	s_setprio 0
	s_add_i32 s2, 0, 0x18000
	v_add_u32_e32 v163, s2, v160
	s_barrier
	ds_read_b128 v[152:155], v163
	ds_read_b128 v[156:159], v163 offset:1024
	ds_read_b128 v[164:167], v163 offset:2048
	ds_read_b128 v[168:171], v163 offset:3072
	s_add_u32 s14, s14, 0x20000
	s_addc_u32 s15, s15, 0
	s_mov_b32 m0, s34
	v_lshl_add_u64 v[224:225], s[14:15], 0, v[0:1]
	ds_read_b128 v[172:175], v162 offset:32768
	ds_read_b128 v[176:179], v162 offset:33792
	ds_read_b128 v[180:183], v162 offset:34816
	ds_read_b128 v[184:187], v162 offset:35840
	ds_read_b128 v[188:191], v162 offset:36864
	ds_read_b128 v[192:195], v162 offset:37888
	ds_read_b128 v[216:219], v162 offset:38912
	ds_read_b128 v[220:223], v162 offset:39936
	global_load_lds_dwordx4 v[224:225], off
	v_lshl_add_u64 v[224:225], s[14:15], 0, v[130:131]
	s_mov_b32 m0, s35
	s_nop 0
	global_load_lds_dwordx4 v[224:225], off
	s_waitcnt lgkmcnt(8)
	s_barrier
	s_waitcnt lgkmcnt(0)
	s_setprio 1
	s_waitcnt lgkmcnt(0)
	v_mfma_f32_16x16x32_bf16 v[126:129], v[152:155], v[172:175], v[126:129]
	v_mfma_f32_16x16x32_bf16 v[98:101], v[164:167], v[172:175], v[98:101]
	v_mfma_f32_16x16x32_bf16 v[122:125], v[152:155], v[180:183], v[122:125]
	v_mfma_f32_16x16x32_bf16 v[90:93], v[164:167], v[180:183], v[90:93]
	v_mfma_f32_16x16x32_bf16 v[118:121], v[152:155], v[188:191], v[118:121]
	v_mfma_f32_16x16x32_bf16 v[86:89], v[164:167], v[188:191], v[86:89]
	v_mfma_f32_16x16x32_bf16 v[114:117], v[152:155], v[216:219], v[114:117]
	v_mfma_f32_16x16x32_bf16 v[82:85], v[164:167], v[216:219], v[82:85]
	v_mfma_f32_16x16x32_bf16 v[126:129], v[156:159], v[176:179], v[126:129]
	v_mfma_f32_16x16x32_bf16 v[98:101], v[168:171], v[176:179], v[98:101]
	v_mfma_f32_16x16x32_bf16 v[122:125], v[156:159], v[184:187], v[122:125]
	v_mfma_f32_16x16x32_bf16 v[90:93], v[168:171], v[184:187], v[90:93]
	v_mfma_f32_16x16x32_bf16 v[118:121], v[156:159], v[192:195], v[118:121]
	v_mfma_f32_16x16x32_bf16 v[86:89], v[168:171], v[192:195], v[86:89]
	v_mfma_f32_16x16x32_bf16 v[114:117], v[156:159], v[220:223], v[114:117]
	v_mfma_f32_16x16x32_bf16 v[82:85], v[168:171], v[220:223], v[82:85]
	s_setprio 0
	s_barrier
	s_add_i32 s3, 0, 0x1c000
	s_add_i32 s2, s2, s18
	v_add_u32_e32 v163, s3, v160
	v_lshl_add_u64 v[214:215], v[214:215], 0, s[64:65]
	s_mov_b32 m0, s2
	ds_read_b128 v[224:227], v163
	ds_read_b128 v[228:231], v163 offset:1024
	ds_read_b128 v[232:235], v163 offset:2048
	ds_read_b128 v[236:239], v163 offset:3072
	global_load_lds_dwordx4 v[214:215], off
	v_lshl_add_u64 v[214:215], v[240:241], 0, s[64:65]
	s_add_i32 m0, s2, 0x2000
	s_nop 0
	global_load_lds_dwordx4 v[214:215], off
	s_barrier
	s_waitcnt lgkmcnt(0)
	s_setprio 1
	s_waitcnt lgkmcnt(0)
	v_mfma_f32_16x16x32_bf16 v[66:69], v[224:227], v[172:175], v[66:69]
	v_mfma_f32_16x16x32_bf16 v[34:37], v[232:235], v[172:175], v[34:37]
	v_mfma_f32_16x16x32_bf16 v[58:61], v[224:227], v[180:183], v[58:61]
	v_mfma_f32_16x16x32_bf16 v[26:29], v[232:235], v[180:183], v[26:29]
	v_mfma_f32_16x16x32_bf16 v[54:57], v[224:227], v[188:191], v[54:57]
	v_mfma_f32_16x16x32_bf16 v[22:25], v[232:235], v[188:191], v[22:25]
	v_mfma_f32_16x16x32_bf16 v[50:53], v[224:227], v[216:219], v[50:53]
	v_mfma_f32_16x16x32_bf16 v[18:21], v[232:235], v[216:219], v[18:21]
	v_mfma_f32_16x16x32_bf16 v[66:69], v[228:231], v[176:179], v[66:69]
	v_mfma_f32_16x16x32_bf16 v[34:37], v[236:239], v[176:179], v[34:37]
	v_mfma_f32_16x16x32_bf16 v[58:61], v[228:231], v[184:187], v[58:61]
	v_mfma_f32_16x16x32_bf16 v[26:29], v[236:239], v[184:187], v[26:29]
	v_mfma_f32_16x16x32_bf16 v[54:57], v[228:231], v[192:195], v[54:57]
	v_mfma_f32_16x16x32_bf16 v[22:25], v[236:239], v[192:195], v[22:25]
	v_mfma_f32_16x16x32_bf16 v[50:53], v[228:231], v[220:223], v[50:53]
	v_mfma_f32_16x16x32_bf16 v[18:21], v[236:239], v[220:223], v[18:21]
	s_setprio 0
	s_mov_b32 m0, s36
	v_lshl_add_u64 v[214:215], v[242:243], 0, s[64:65]
	s_barrier
	ds_read_b128 v[172:175], v162 offset:49152
	ds_read_b128 v[176:179], v162 offset:50176
	ds_read_b128 v[180:183], v162 offset:51200
	ds_read_b128 v[184:187], v162 offset:52224
	ds_read_b128 v[188:191], v162 offset:53248
	ds_read_b128 v[192:195], v162 offset:54272
	ds_read_b128 v[216:219], v162 offset:55296
	ds_read_b128 v[220:223], v162 offset:56320
	global_load_lds_dwordx4 v[214:215], off
	v_lshl_add_u64 v[214:215], v[244:245], 0, s[64:65]
	s_mov_b32 m0, s37
	s_nop 0
	global_load_lds_dwordx4 v[214:215], off
	s_barrier
; #define PG8_STAGE(bufoff, gbase, voff) do { _Pragma("unroll") for (int _i = 0; _i < 2; ++_i) \
;         __builtin_amdgcn_global_load_lds((const unsigned*)((const char*)(gbase) + (voff)[_i]), (LAS unsigned*)(lds + (bufoff) + ldsw + _i * 8192), 16, 0, 0); } while (0)
; #define PG8_STAGE_A(bufoff, gbase, h, vv) do { if constexpr (GATHER) { _Pragma("unroll") for (int _i = 0; _i < 2; ++_i) \
;         __builtin_amdgcn_global_load_lds((const unsigned*)((const char*)(gbase) + (vv)[h][_i]), (LAS unsigned*)(lds + (bufoff) + ldsw + _i * 8192), 16, 0, 0); } \
;         else { PG8_STAGE(bufoff, (gbase) + (h) * hstepA, voffA); } } while (0)
; #define PG8_WAIT_V(n) asm volatile("s_waitcnt vmcnt(" #n ")" ::: "memory")
; #define PG8_BAR __builtin_amdgcn_s_barrier()
; template <class Epi, class Sched>
; __device__ __forceinline__ void gemm_phase(LAS unsigned char* lds, const int K, const int lda, const int ldb, const Sched& S, const Epi& E) {
;     ...
;             PG8_WAIT_V(6); PG8_BAR; PG8_MMA(1, 1, At, B1); PG8_BAR;
;             PG8_LDB(B0, 1, 0); PG8_SCHED; PG8_LDA(At, 1, 0); PG8_STAGE_A(PG8_SA(0, 1), a2, 1, vcur);
;             PG8_WAIT_L(8); PG8_BAR; PG8_WAIT_L(0); PG8_MMA(0, 0, At, B0); PG8_BAR; PG8_SCHED;
;             PG8_LDB(B1, 1, 1); PG8_STAGE(PG8_SB(1, 0), b3, voffB);
;             PG8_BAR; PG8_WAIT_L(0); PG8_MMA(0, 1, At, B1); PG8_BAR;
;             PG8_LDA(At, 1, 1); PG8_STAGE_A(PG8_SA(1, 0), a3, 0, vcur);
;             PG8_BAR; PG8_WAIT_L(0); PG8_MMA(1, 0, At, B0); PG8_BAR; PG8_SCHED;
;             PG8_STAGE(PG8_SB(1, 1), b3 + hstepB, voffB);
;             PG8_WAIT_V(6); PG8_BAR; PG8_MMA(1, 1, At, B1); PG8_BAR;
;         }
;     __device__ __forceinline__ void operator()(const Acc& acc, const Unit& u, int wr, int wc, int fr, int fq) const {
;         const int row0 = wr * 64 + fr, col0 = u.pn * BM + wc * 32 + 4 * fq;
; #pragma unroll
;         for (int bj = 0; bj < 2; ++bj)
; #pragma unroll
;             for (int n = 0; n < 2; ++n) { const int col = col0 + bj * HALF + n * 16;
;                 const f32x4 g = *(const f32x4*)(gate + col) * (1.f / 256.f);
; #pragma unroll
;                 for (int ai = 0; ai < 2; ++ai)
; #pragma unroll
;                     for (int m = 0; m < 4; ++m) { f32x4* p = (f32x4*)(X + (size_t)(SEQ + row0 + ai * HALF + m * 16) * D + col); *p = *p + g * acc[ai][bj][m][n]; }
;                 __builtin_amdgcn_sched_barrier(0); }
	s_waitcnt lgkmcnt(0)
	s_setprio 1
	s_waitcnt lgkmcnt(0)
	v_mfma_f32_16x16x32_bf16 v[110:113], v[152:155], v[172:175], v[110:113]
	v_mfma_f32_16x16x32_bf16 v[78:81], v[164:167], v[172:175], v[78:81]
	v_mfma_f32_16x16x32_bf16 v[106:109], v[152:155], v[180:183], v[106:109]
	v_mfma_f32_16x16x32_bf16 v[74:77], v[164:167], v[180:183], v[74:77]
	v_mfma_f32_16x16x32_bf16 v[102:105], v[152:155], v[188:191], v[102:105]
	v_mfma_f32_16x16x32_bf16 v[70:73], v[164:167], v[188:191], v[70:73]
	v_mfma_f32_16x16x32_bf16 v[94:97], v[152:155], v[216:219], v[94:97]
	v_mfma_f32_16x16x32_bf16 v[62:65], v[164:167], v[216:219], v[62:65]
	v_mfma_f32_16x16x32_bf16 v[110:113], v[156:159], v[176:179], v[110:113]
	v_mfma_f32_16x16x32_bf16 v[78:81], v[168:171], v[176:179], v[78:81]
	v_mfma_f32_16x16x32_bf16 v[106:109], v[156:159], v[184:187], v[106:109]
	v_mfma_f32_16x16x32_bf16 v[74:77], v[168:171], v[184:187], v[74:77]
	v_mfma_f32_16x16x32_bf16 v[102:105], v[156:159], v[192:195], v[102:105]
	v_mfma_f32_16x16x32_bf16 v[70:73], v[168:171], v[192:195], v[70:73]
	v_mfma_f32_16x16x32_bf16 v[94:97], v[156:159], v[220:223], v[94:97]
	v_mfma_f32_16x16x32_bf16 v[62:65], v[168:171], v[220:223], v[62:65]
	s_setprio 0
	s_barrier
	s_add_u32 s12, s12, 0x20080
	s_addc_u32 s13, s13, 0
	s_add_i32 s2, s3, s18
	v_lshl_add_u64 v[152:153], s[12:13], 0, v[0:1]
	s_mov_b32 m0, s2
	s_nop 0
	global_load_lds_dwordx4 v[152:153], off
	v_lshl_add_u64 v[152:153], s[12:13], 0, v[130:131]
	s_add_i32 m0, s2, 0x2000
	s_nop 0
	global_load_lds_dwordx4 v[152:153], off
	s_waitcnt vmcnt(6)
	s_barrier
	s_setprio 1
	v_mfma_f32_16x16x32_bf16 v[46:49], v[224:227], v[172:175], v[46:49]
	v_mfma_f32_16x16x32_bf16 v[14:17], v[232:235], v[172:175], v[14:17]
	v_mfma_f32_16x16x32_bf16 v[42:45], v[224:227], v[180:183], v[42:45]
	v_mfma_f32_16x16x32_bf16 v[10:13], v[232:235], v[180:183], v[10:13]
	v_mfma_f32_16x16x32_bf16 v[38:41], v[224:227], v[188:191], v[38:41]
	v_mfma_f32_16x16x32_bf16 v[6:9], v[232:235], v[188:191], v[6:9]
	v_mfma_f32_16x16x32_bf16 v[30:33], v[224:227], v[216:219], v[30:33]
	v_mfma_f32_16x16x32_bf16 v[2:5], v[232:235], v[216:219], v[2:5]
	v_mfma_f32_16x16x32_bf16 v[46:49], v[228:231], v[176:179], v[46:49]
	v_mfma_f32_16x16x32_bf16 v[14:17], v[236:239], v[176:179], v[14:17]
	v_mfma_f32_16x16x32_bf16 v[42:45], v[228:231], v[184:187], v[42:45]
	v_mfma_f32_16x16x32_bf16 v[10:13], v[236:239], v[184:187], v[10:13]
	v_mfma_f32_16x16x32_bf16 v[38:41], v[228:231], v[192:195], v[38:41]
	v_mfma_f32_16x16x32_bf16 v[6:9], v[236:239], v[192:195], v[6:9]
	v_mfma_f32_16x16x32_bf16 v[30:33], v[228:231], v[220:223], v[30:33]
	v_mfma_f32_16x16x32_bf16 v[2:5], v[236:239], v[220:223], v[2:5]
	s_setprio 0
	s_add_i32 s43, s43, 2
	s_add_u32 s10, s10, 0x100
	s_addc_u32 s11, s11, 0
	s_add_u32 s41, s41, 0x100
	s_addc_u32 s42, s42, 0
	s_cmp_gt_u32 s43, 5
	s_barrier
	s_cbranch_scc0 .LBB0_270
	v_lshl_or_b32 v154, s40, 8, v161
	v_ashrrev_i32_e32 v155, 31, v154
	v_lshlrev_b64 v[168:169], 2, v[154:155]
	v_lshl_add_u64 v[152:153], s[0:1], 0, v[168:169]
	global_load_dwordx4 v[164:167], v[152:153], off
	s_mov_b32 s2, 0x3b800000
	v_lshl_add_u64 v[152:153], v[132:133], 0, v[168:169]
	s_waitcnt vmcnt(0)
	v_pk_mul_f32 v[156:157], v[166:167], s[2:3] op_sel_hi:[1,0]
	v_pk_mul_f32 v[158:159], v[164:165], s[2:3] op_sel_hi:[1,0]
	global_load_dwordx4 v[164:167], v[152:153], off
	s_waitcnt vmcnt(0)
	v_pk_fma_f32 v[128:129], v[128:129], v[156:157], v[166:167]
	v_pk_fma_f32 v[126:127], v[126:127], v[158:159], v[164:165]
	global_store_dwordx4 v[152:153], v[126:129], off
	s_nop 1
	v_lshl_add_u64 v[126:127], v[134:135], 0, v[168:169]
	global_load_dwordx4 v[164:167], v[126:127], off
	s_waitcnt vmcnt(0)
	v_pk_fma_f32 v[124:125], v[124:125], v[156:157], v[166:167]
	v_pk_fma_f32 v[122:123], v[122:123], v[158:159], v[164:165]
	global_store_dwordx4 v[126:127], v[122:125], off
	s_nop 1
	v_lshl_add_u64 v[122:123], v[136:137], 0, v[168:169]
	global_load_dwordx4 v[164:167], v[122:123], off
	s_waitcnt vmcnt(0)
	v_pk_fma_f32 v[120:121], v[120:121], v[156:157], v[166:167]
	v_pk_fma_f32 v[118:119], v[118:119], v[158:159], v[164:165]
	global_store_dwordx4 v[122:123], v[118:121], off
	s_nop 1
	v_lshl_add_u64 v[118:119], v[138:139], 0, v[168:169]
	global_load_dwordx4 v[164:167], v[118:119], off
	s_waitcnt vmcnt(0)
	v_pk_fma_f32 v[116:117], v[116:117], v[156:157], v[166:167]
	v_pk_fma_f32 v[114:115], v[114:115], v[158:159], v[164:165]
	global_store_dwordx4 v[118:119], v[114:117], off
	s_nop 1
	v_lshl_add_u64 v[114:115], v[140:141], 0, v[168:169]
	global_load_dwordx4 v[164:167], v[114:115], off
	s_waitcnt vmcnt(0)
	v_pk_fma_f32 v[112:113], v[112:113], v[156:157], v[166:167]
	v_pk_fma_f32 v[110:111], v[110:111], v[158:159], v[164:165]
	global_store_dwordx4 v[114:115], v[110:113], off
	s_nop 1
	v_lshl_add_u64 v[110:111], v[142:143], 0, v[168:169]
	global_load_dwordx4 v[164:167], v[110:111], off
	s_waitcnt vmcnt(0)
	v_pk_fma_f32 v[108:109], v[108:109], v[156:157], v[166:167]
	v_pk_fma_f32 v[106:107], v[106:107], v[158:159], v[164:165]
	global_store_dwordx4 v[110:111], v[106:109], off
	s_nop 1
	v_lshl_add_u64 v[106:107], v[144:145], 0, v[168:169]
	global_load_dwordx4 v[164:167], v[106:107], off
	s_waitcnt vmcnt(0)
	v_pk_fma_f32 v[104:105], v[104:105], v[156:157], v[166:167]
	v_pk_fma_f32 v[102:103], v[102:103], v[158:159], v[164:165]
	global_store_dwordx4 v[106:107], v[102:105], off
	s_nop 1
	v_lshl_add_u64 v[102:103], v[146:147], 0, v[168:169]
	global_load_dwordx4 v[164:167], v[102:103], off
	s_waitcnt vmcnt(0)
;     __device__ __forceinline__ void operator()(const Acc& acc, const Unit& u, int wr, int wc, int fr, int fq) const {
;     ...
;         for (int bj = 0; bj < 2; ++bj)
; #pragma unroll
;             for (int n = 0; n < 2; ++n) { const int col = col0 + bj * HALF + n * 16;
;                 const f32x4 g = *(const f32x4*)(gate + col) * (1.f / 256.f);
; #pragma unroll
;                 for (int ai = 0; ai < 2; ++ai)
; #pragma unroll
;                     for (int m = 0; m < 4; ++m) { f32x4* p = (f32x4*)(X + (size_t)(SEQ + row0 + ai * HALF + m * 16) * D + col); *p = *p + g * acc[ai][bj][m][n]; }
;                 __builtin_amdgcn_sched_barrier(0); }
	v_pk_fma_f32 v[96:97], v[96:97], v[156:157], v[166:167]
	v_pk_fma_f32 v[94:95], v[94:95], v[158:159], v[164:165]
	global_store_dwordx4 v[102:103], v[94:97], off
	s_nop 1
	v_or_b32_e32 v94, 16, v154
	v_ashrrev_i32_e32 v95, 31, v94
	v_lshl_add_u64 v[94:95], v[94:95], 2, s[0:1]
	global_load_dwordx4 v[94:97], v[94:95], off
	s_waitcnt vmcnt(0)
	v_pk_mul_f32 v[104:105], v[96:97], s[2:3] op_sel_hi:[1,0]
	v_pk_mul_f32 v[108:109], v[94:95], s[2:3] op_sel_hi:[1,0]
	global_load_dwordx4 v[172:175], v[152:153], off offset:64
	global_load_dwordx4 v[176:179], v[126:127], off offset:64
	global_load_dwordx4 v[180:183], v[122:123], off offset:64
	global_load_dwordx4 v[184:187], v[118:119], off offset:64
	global_load_dwordx4 v[188:191], v[114:115], off offset:64
	global_load_dwordx4 v[192:195], v[110:111], off offset:64
	global_load_dwordx4 v[216:219], v[106:107], off offset:64
	global_load_dwordx4 v[220:223], v[102:103], off offset:64
	s_waitcnt vmcnt(7)
	v_pk_fma_f32 v[96:97], v[100:101], v[104:105], v[174:175]
	v_pk_fma_f32 v[94:95], v[98:99], v[108:109], v[172:173]
	global_store_dwordx4 v[152:153], v[94:97], off offset:64
	s_waitcnt vmcnt(7)
	v_pk_fma_f32 v[92:93], v[92:93], v[104:105], v[178:179]
	v_pk_fma_f32 v[90:91], v[90:91], v[108:109], v[176:177]
	global_store_dwordx4 v[126:127], v[90:93], off offset:64
	s_waitcnt vmcnt(7)
	v_pk_fma_f32 v[88:89], v[88:89], v[104:105], v[182:183]
	v_pk_fma_f32 v[86:87], v[86:87], v[108:109], v[180:181]
	global_store_dwordx4 v[122:123], v[86:89], off offset:64
	s_waitcnt vmcnt(7)
	v_pk_fma_f32 v[84:85], v[84:85], v[104:105], v[186:187]
	v_pk_fma_f32 v[82:83], v[82:83], v[108:109], v[184:185]
	global_store_dwordx4 v[118:119], v[82:85], off offset:64
	s_waitcnt vmcnt(7)
	v_pk_fma_f32 v[80:81], v[80:81], v[104:105], v[190:191]
	v_pk_fma_f32 v[78:79], v[78:79], v[108:109], v[188:189]
	global_store_dwordx4 v[114:115], v[78:81], off offset:64
	s_waitcnt vmcnt(7)
	v_pk_fma_f32 v[76:77], v[76:77], v[104:105], v[194:195]
	v_pk_fma_f32 v[74:75], v[74:75], v[108:109], v[192:193]
	global_store_dwordx4 v[110:111], v[74:77], off offset:64
	s_waitcnt vmcnt(7)
	v_pk_fma_f32 v[72:73], v[72:73], v[104:105], v[218:219]
	v_pk_fma_f32 v[70:71], v[70:71], v[108:109], v[216:217]
	global_store_dwordx4 v[106:107], v[70:73], off offset:64
	s_waitcnt vmcnt(7)
	v_pk_fma_f32 v[64:65], v[64:65], v[104:105], v[222:223]
	v_pk_fma_f32 v[62:63], v[62:63], v[108:109], v[220:221]
	global_store_dwordx4 v[102:103], v[62:65], off offset:64
	s_nop 1
	v_or_b32_e32 v62, 0x80, v154
	v_ashrrev_i32_e32 v63, 31, v62
	v_lshl_add_u64 v[62:63], v[62:63], 2, s[0:1]
	global_load_dwordx4 v[62:65], v[62:63], off
	s_waitcnt vmcnt(0)
	v_pk_mul_f32 v[70:71], v[64:65], s[2:3] op_sel_hi:[1,0]
	v_pk_mul_f32 v[72:73], v[62:63], s[2:3] op_sel_hi:[1,0]
	global_load_dwordx4 v[172:175], v[152:153], off offset:512
	global_load_dwordx4 v[176:179], v[126:127], off offset:512
	global_load_dwordx4 v[180:183], v[122:123], off offset:512
	global_load_dwordx4 v[184:187], v[118:119], off offset:512
	global_load_dwordx4 v[188:191], v[114:115], off offset:512
	global_load_dwordx4 v[192:195], v[110:111], off offset:512
	global_load_dwordx4 v[216:219], v[106:107], off offset:512
	global_load_dwordx4 v[220:223], v[102:103], off offset:512
	s_waitcnt vmcnt(7)
	v_pk_fma_f32 v[64:65], v[68:69], v[70:71], v[174:175]
	v_pk_fma_f32 v[62:63], v[66:67], v[72:73], v[172:173]
	global_store_dwordx4 v[152:153], v[62:65], off offset:512
	s_waitcnt vmcnt(7)
	v_pk_fma_f32 v[60:61], v[60:61], v[70:71], v[178:179]
	v_pk_fma_f32 v[58:59], v[58:59], v[72:73], v[176:177]
	global_store_dwordx4 v[126:127], v[58:61], off offset:512
	s_waitcnt vmcnt(7)
; #define PG8_WAIT_V(n) asm volatile("s_waitcnt vmcnt(" #n ")" ::: "memory")
; #define PG8_BAR __builtin_amdgcn_s_barrier()
; template <class Epi, class Sched>
; __device__ __forceinline__ void gemm_phase(LAS unsigned char* lds, const int K, const int lda, const int ldb, const Sched& S, const Epi& E) {
;     ...
;         if constexpr (!Epi::AFTER_DRAIN) E(acc, cur, wr, wc, fr, fq);
;         if (!has_next) break;
; #pragma unroll
;         for (int a = 0; a < 2; ++a)
; #pragma unroll
;             for (int b = 0; b < 2; ++b)
; #pragma unroll
;                 for (int m = 0; m < 4; ++m)
; #pragma unroll
;                     for (int n = 0; n < 2; ++n) acc[a][b][m][n] = (f32x4){0.f, 0.f, 0.f, 0.f};
;         cur = nxt; cA = nA; cB = nB; ++ui;
;     }
;     PG8_WAIT_V(0);
;     if (wr == 0) PG8_BAR;
;     PG8_BAR;
;     __device__ __forceinline__ void operator()(const Acc& acc, const Unit& u, int wr, int wc, int fr, int fq) const {
;     ...
;             for (int n = 0; n < 2; ++n) { const int col = col0 + bj * HALF + n * 16;
;                 const f32x4 g = *(const f32x4*)(gate + col) * (1.f / 256.f);
; #pragma unroll
;                 for (int ai = 0; ai < 2; ++ai)
; #pragma unroll
;                     for (int m = 0; m < 4; ++m) { f32x4* p = (f32x4*)(X + (size_t)(SEQ + row0 + ai * HALF + m * 16) * D + col); *p = *p + g * acc[ai][bj][m][n]; }
;                 __builtin_amdgcn_sched_barrier(0); }
	v_pk_fma_f32 v[56:57], v[56:57], v[70:71], v[182:183]
	v_pk_fma_f32 v[54:55], v[54:55], v[72:73], v[180:181]
	global_store_dwordx4 v[122:123], v[54:57], off offset:512
	s_waitcnt vmcnt(7)
	v_pk_fma_f32 v[52:53], v[52:53], v[70:71], v[186:187]
	v_pk_fma_f32 v[50:51], v[50:51], v[72:73], v[184:185]
	global_store_dwordx4 v[118:119], v[50:53], off offset:512
	s_waitcnt vmcnt(7)
	v_pk_fma_f32 v[48:49], v[48:49], v[70:71], v[190:191]
	v_pk_fma_f32 v[46:47], v[46:47], v[72:73], v[188:189]
	global_store_dwordx4 v[114:115], v[46:49], off offset:512
	s_waitcnt vmcnt(7)
	v_pk_fma_f32 v[44:45], v[44:45], v[70:71], v[194:195]
	v_pk_fma_f32 v[42:43], v[42:43], v[72:73], v[192:193]
	global_store_dwordx4 v[110:111], v[42:45], off offset:512
	s_waitcnt vmcnt(7)
	v_pk_fma_f32 v[40:41], v[40:41], v[70:71], v[218:219]
	v_pk_fma_f32 v[38:39], v[38:39], v[72:73], v[216:217]
	global_store_dwordx4 v[106:107], v[38:41], off offset:512
	s_waitcnt vmcnt(7)
	v_pk_fma_f32 v[32:33], v[32:33], v[70:71], v[222:223]
	v_pk_fma_f32 v[30:31], v[30:31], v[72:73], v[220:221]
	global_store_dwordx4 v[102:103], v[30:33], off offset:512
	s_nop 1
	v_or_b32_e32 v30, 0x90, v154
	v_ashrrev_i32_e32 v31, 31, v30
	v_lshl_add_u64 v[30:31], v[30:31], 2, s[0:1]
	global_load_dwordx4 v[30:33], v[30:31], off
	s_waitcnt vmcnt(0)
	v_pk_mul_f32 v[38:39], v[32:33], s[2:3] op_sel_hi:[1,0]
	v_pk_mul_f32 v[40:41], v[30:31], s[2:3] op_sel_hi:[1,0]
	global_load_dwordx4 v[172:175], v[152:153], off offset:576
	global_load_dwordx4 v[176:179], v[126:127], off offset:576
	global_load_dwordx4 v[180:183], v[122:123], off offset:576
	global_load_dwordx4 v[184:187], v[118:119], off offset:576
	global_load_dwordx4 v[188:191], v[114:115], off offset:576
	global_load_dwordx4 v[192:195], v[110:111], off offset:576
	global_load_dwordx4 v[216:219], v[106:107], off offset:576
	global_load_dwordx4 v[220:223], v[102:103], off offset:576
	s_waitcnt vmcnt(7)
	v_pk_fma_f32 v[32:33], v[36:37], v[38:39], v[174:175]
	v_pk_fma_f32 v[30:31], v[34:35], v[40:41], v[172:173]
	global_store_dwordx4 v[152:153], v[30:33], off offset:576
	s_waitcnt vmcnt(7)
	v_pk_fma_f32 v[28:29], v[28:29], v[38:39], v[178:179]
	v_pk_fma_f32 v[26:27], v[26:27], v[40:41], v[176:177]
	global_store_dwordx4 v[126:127], v[26:29], off offset:576
	s_waitcnt vmcnt(7)
	v_pk_fma_f32 v[24:25], v[24:25], v[38:39], v[182:183]
	v_pk_fma_f32 v[22:23], v[22:23], v[40:41], v[180:181]
	global_store_dwordx4 v[122:123], v[22:25], off offset:576
	s_waitcnt vmcnt(7)
	v_pk_fma_f32 v[20:21], v[20:21], v[38:39], v[186:187]
	v_pk_fma_f32 v[18:19], v[18:19], v[40:41], v[184:185]
	global_store_dwordx4 v[118:119], v[18:21], off offset:576
	s_waitcnt vmcnt(7)
	v_pk_fma_f32 v[16:17], v[16:17], v[38:39], v[190:191]
	v_pk_fma_f32 v[14:15], v[14:15], v[40:41], v[188:189]
	global_store_dwordx4 v[114:115], v[14:17], off offset:576
	s_waitcnt vmcnt(7)
	v_pk_fma_f32 v[12:13], v[12:13], v[38:39], v[194:195]
	v_pk_fma_f32 v[10:11], v[10:11], v[40:41], v[192:193]
	global_store_dwordx4 v[110:111], v[10:13], off offset:576
	s_waitcnt vmcnt(7)
	v_pk_fma_f32 v[8:9], v[8:9], v[38:39], v[218:219]
	v_pk_fma_f32 v[6:7], v[6:7], v[40:41], v[216:217]
	global_store_dwordx4 v[106:107], v[6:9], off offset:576
	s_waitcnt vmcnt(7)
	v_pk_fma_f32 v[4:5], v[4:5], v[38:39], v[222:223]
	v_pk_fma_f32 v[2:3], v[2:3], v[40:41], v[220:221]
	global_store_dwordx4 v[102:103], v[2:5], off offset:576
	s_and_b64 vcc, exec, s[4:5]
	s_mov_b32 s40, s39
	s_mov_b64 s[12:13], s[8:9]
	s_mov_b64 s[10:11], s[6:7]
	s_cbranch_vccz .LBB0_267
	s_waitcnt vmcnt(0)
	s_cmpk_gt_u32 s17, 0xff
	s_cbranch_scc1 .LBB0_274
	s_barrier

;     __device__ __forceinline__ void operator()(const Acc& acc, const Unit& u, int wr, int wc, int fr, int fq) const {
;         const int col0 = u.pn * BM + wc * 32 + 4 * fq;
; #pragma unroll
;         for (int m = 0; m < 4; ++m) { const int kb = wr * 64 + m * 16 + fr;
; #pragma unroll
;             for (int bj = 0; bj < 2; ++bj)
; #pragma unroll
;                 for (int n = 0; n < 2; ++n) { const int q = col0 + bj * HALF + n * 16, ka = q >> 10, nn = q & 1023;
;                     const f32x4 g = *(const f32x4*)(gate + nn) * (1.f / 2048.f);
;                     const size_t o = (size_t)(ka + 128 * kb) * D + nn; *(f32x4*)(X + o) = *(const f32x4*)(Xin + o) + g * acc[0][bj][m][n]; }
;             if (m & 1) __builtin_amdgcn_sched_barrier(0); }
.Lgx_c_pre:
	s_ashr_i32 s8, s52, 2
	s_lshl_b32 s2, s52, 8
	v_add_u32_e32 v68, s8, v75
	s_and_b32 s2, s2, 0x300
	v_ashrrev_i32_e32 v69, 31, v68
	v_or_b32_e32 v81, s2, v79
	v_lshlrev_b64 v[72:73], 10, v[68:69]
	v_or_b32_e32 v82, v72, v81
	v_mov_b32_e32 v83, v73
	v_readlane_b32 s10, v253, 28
	v_lshlrev_b32_e32 v92, 2, v81
	v_lshlrev_b64 v[86:87], 2, v[82:83]
	v_readlane_b32 s11, v253, 29
	global_load_dwordx4 v[68:71], v92, s[92:93]
	s_mov_b32 s2, 0x3a000000
	v_lshl_add_u64 v[88:89], s[10:11], 0, v[86:87]
	global_load_dwordx4 v[140:143], v[88:89], off
	global_load_dwordx4 v[144:147], v[88:89], off offset:64
	global_load_dwordx4 v[148:151], v[88:89], off offset:512
	global_load_dwordx4 v[152:155], v[88:89], off offset:576
	v_mov_b32_e32 v91, v73
	s_waitcnt vmcnt(0)
	v_pk_mul_f32 v[68:69], v[68:69], s[2:3] op_sel_hi:[1,0]
	v_pk_mul_f32 v[70:71], v[70:71], s[2:3] op_sel_hi:[1,0]
	v_pk_fma_f32 v[62:63], v[62:63], v[68:69], v[140:141]
	v_pk_fma_f32 v[64:65], v[64:65], v[70:71], v[142:143]
	v_lshl_add_u64 v[82:83], s[22:23], 0, v[86:87]
	global_store_dwordx4 v[82:83], v[62:65], off
	v_or_b32_e32 v82, 16, v81
	v_lshlrev_b32_e32 v93, 2, v82
	global_load_dwordx4 v[62:65], v93, s[92:93]
	v_or_b32_e32 v90, v72, v82
	v_or_b32_e32 v83, 0x80, v81
	v_lshlrev_b32_e32 v94, 2, v83
	s_waitcnt vmcnt(0)
	v_pk_mul_f32 v[62:63], v[62:63], s[2:3] op_sel_hi:[1,0]
	v_pk_mul_f32 v[64:65], v[64:65], s[2:3] op_sel_hi:[1,0]
	v_pk_fma_f32 v[58:59], v[58:59], v[62:63], v[144:145]
	v_pk_fma_f32 v[60:61], v[60:61], v[64:65], v[146:147]
	v_lshl_add_u64 v[84:85], v[90:91], 2, s[22:23]
	global_store_dwordx4 v[84:85], v[58:61], off
	global_load_dwordx4 v[58:61], v94, s[92:93]
	v_or_b32_e32 v90, v72, v83
	s_waitcnt vmcnt(0)
	v_pk_mul_f32 v[58:59], v[58:59], s[2:3] op_sel_hi:[1,0]
	v_pk_mul_f32 v[60:61], v[60:61], s[2:3] op_sel_hi:[1,0]
	v_pk_fma_f32 v[54:55], v[54:55], v[58:59], v[148:149]
	v_pk_fma_f32 v[56:57], v[56:57], v[60:61], v[150:151]
	v_lshl_add_u64 v[84:85], v[90:91], 2, s[22:23]
	global_store_dwordx4 v[84:85], v[54:57], off
	s_nop 1
	v_or_b32_e32 v54, 0x90, v81
	v_lshlrev_b32_e32 v55, 2, v54
	global_load_dwordx4 v[84:87], v55, s[92:93]
	v_or_b32_e32 v72, v72, v54
	v_lshl_add_u64 v[72:73], v[72:73], 2, s[22:23]
	s_waitcnt vmcnt(0)
	v_pk_mul_f32 v[56:57], v[84:85], s[2:3] op_sel_hi:[1,0]
	v_pk_mul_f32 v[90:91], v[86:87], s[2:3] op_sel_hi:[1,0]
	s_waitcnt vmcnt(0)
	v_pk_fma_f32 v[52:53], v[52:53], v[90:91], v[154:155]
	v_pk_fma_f32 v[50:51], v[50:51], v[56:57], v[152:153]
	global_store_dwordx4 v[72:73], v[50:53], off
	s_nop 1
	v_add_u32_e32 v50, s8, v76
	v_ashrrev_i32_e32 v51, 31, v50
	v_lshlrev_b64 v[72:73], 10, v[50:51]
	v_or_b32_e32 v50, v72, v81
	v_mov_b32_e32 v51, v73
	v_lshlrev_b64 v[84:85], 2, v[50:51]
	v_lshl_add_u64 v[86:87], s[10:11], 0, v[84:85]
	global_load_dwordx4 v[140:143], v[86:87], off
	global_load_dwordx4 v[144:147], v[86:87], off offset:64
	global_load_dwordx4 v[148:151], v[86:87], off offset:512
	global_load_dwordx4 v[152:155], v[86:87], off offset:576
	s_waitcnt vmcnt(3)
	v_pk_fma_f32 v[48:49], v[48:49], v[70:71], v[142:143]
	v_pk_fma_f32 v[46:47], v[46:47], v[68:69], v[140:141]
	v_lshl_add_u64 v[50:51], s[22:23], 0, v[84:85]
	global_store_dwordx4 v[50:51], v[46:49], off
	v_or_b32_e32 v50, v72, v82
	v_mov_b32_e32 v51, v73
	s_waitcnt vmcnt(3)
	v_pk_fma_f32 v[44:45], v[44:45], v[64:65], v[146:147]
	v_pk_fma_f32 v[42:43], v[42:43], v[62:63], v[144:145]
	v_lshl_add_u64 v[46:47], v[50:51], 2, s[22:23]
	global_store_dwordx4 v[46:47], v[42:45], off
	v_or_b32_e32 v46, v72, v83
	v_mov_b32_e32 v47, v73
	v_or_b32_e32 v72, v72, v54
	s_waitcnt vmcnt(3)
	v_pk_fma_f32 v[40:41], v[40:41], v[60:61], v[150:151]
	v_pk_fma_f32 v[38:39], v[38:39], v[58:59], v[148:149]
	v_lshl_add_u64 v[42:43], v[46:47], 2, s[22:23]
	global_store_dwordx4 v[42:43], v[38:41], off
	s_waitcnt vmcnt(3)
;     __device__ __forceinline__ void operator()(const Acc& acc, const Unit& u, int wr, int wc, int fr, int fq) const {
;         const int col0 = u.pn * BM + wc * 32 + 4 * fq;
; #pragma unroll
;         for (int m = 0; m < 4; ++m) { const int kb = wr * 64 + m * 16 + fr;
; #pragma unroll
;             for (int bj = 0; bj < 2; ++bj)
; #pragma unroll
;                 for (int n = 0; n < 2; ++n) { const int q = col0 + bj * HALF + n * 16, ka = q >> 10, nn = q & 1023;
;                     const f32x4 g = *(const f32x4*)(gate + nn) * (1.f / 2048.f);
;                     const size_t o = (size_t)(ka + 128 * kb) * D + nn; *(f32x4*)(X + o) = *(const f32x4*)(Xin + o) + g * acc[0][bj][m][n]; }
;             if (m & 1) __builtin_amdgcn_sched_barrier(0); }
	v_pk_fma_f32 v[36:37], v[36:37], v[90:91], v[154:155]
	v_pk_fma_f32 v[34:35], v[34:35], v[56:57], v[152:153]
	v_lshl_add_u64 v[38:39], v[72:73], 2, s[22:23]
	global_store_dwordx4 v[38:39], v[34:37], off
	s_nop 1
	v_add_u32_e32 v34, s8, v77
	v_ashrrev_i32_e32 v35, 31, v34
	v_lshlrev_b64 v[42:43], 10, v[34:35]
	v_or_b32_e32 v38, v42, v81
	v_mov_b32_e32 v39, v43
	v_lshlrev_b64 v[44:45], 2, v[38:39]
	global_load_dwordx4 v[34:37], v92, s[92:93]
	v_lshl_add_u64 v[46:47], s[10:11], 0, v[44:45]
	global_load_dwordx4 v[140:143], v[46:47], off
	global_load_dwordx4 v[144:147], v[46:47], off offset:64
	global_load_dwordx4 v[148:151], v[46:47], off offset:512
	global_load_dwordx4 v[152:155], v[46:47], off offset:576
	s_waitcnt vmcnt(0)
	v_pk_mul_f32 v[34:35], v[34:35], s[2:3] op_sel_hi:[1,0]
	v_pk_mul_f32 v[36:37], v[36:37], s[2:3] op_sel_hi:[1,0]
	v_pk_fma_f32 v[30:31], v[30:31], v[34:35], v[140:141]
	v_pk_fma_f32 v[32:33], v[32:33], v[36:37], v[142:143]
	v_lshl_add_u64 v[38:39], s[22:23], 0, v[44:45]
	global_store_dwordx4 v[38:39], v[30:33], off
	global_load_dwordx4 v[30:33], v93, s[92:93]
	v_or_b32_e32 v44, v42, v82
	v_mov_b32_e32 v45, v43
	s_waitcnt vmcnt(0)
	v_pk_mul_f32 v[30:31], v[30:31], s[2:3] op_sel_hi:[1,0]
	v_pk_mul_f32 v[32:33], v[32:33], s[2:3] op_sel_hi:[1,0]
	v_pk_fma_f32 v[26:27], v[26:27], v[30:31], v[144:145]
	v_pk_fma_f32 v[28:29], v[28:29], v[32:33], v[146:147]
	v_lshl_add_u64 v[38:39], v[44:45], 2, s[22:23]
	global_store_dwordx4 v[38:39], v[26:29], off
	global_load_dwordx4 v[26:29], v94, s[92:93]
	v_or_b32_e32 v44, v42, v83
	v_or_b32_e32 v42, v42, v54
	s_waitcnt vmcnt(0)
	v_pk_mul_f32 v[38:39], v[26:27], s[2:3] op_sel_hi:[1,0]
	v_pk_mul_f32 v[40:41], v[28:29], s[2:3] op_sel_hi:[1,0]
	s_waitcnt vmcnt(0)
	v_pk_fma_f32 v[24:25], v[24:25], v[40:41], v[150:151]
	v_pk_fma_f32 v[22:23], v[22:23], v[38:39], v[148:149]
	v_lshl_add_u64 v[26:27], v[44:45], 2, s[22:23]
	global_store_dwordx4 v[26:27], v[22:25], off
	global_load_dwordx4 v[22:25], v55, s[92:93]
	s_waitcnt vmcnt(0)
	v_pk_mul_f32 v[26:27], v[22:23], s[2:3] op_sel_hi:[1,0]
	v_pk_mul_f32 v[28:29], v[24:25], s[2:3] op_sel_hi:[1,0]
	s_waitcnt vmcnt(0)
	v_pk_fma_f32 v[20:21], v[20:21], v[28:29], v[154:155]
	v_pk_fma_f32 v[18:19], v[18:19], v[26:27], v[152:153]
	v_lshl_add_u64 v[22:23], v[42:43], 2, s[22:23]
	global_store_dwordx4 v[22:23], v[18:21], off
	s_nop 1
	v_add_u32_e32 v18, s8, v78
	v_ashrrev_i32_e32 v19, 31, v18
	v_lshlrev_b64 v[22:23], 10, v[18:19]
	v_or_b32_e32 v18, v22, v81
	v_mov_b32_e32 v19, v23
	v_lshlrev_b64 v[24:25], 2, v[18:19]
	v_lshl_add_u64 v[42:43], s[10:11], 0, v[24:25]
	global_load_dwordx4 v[140:143], v[42:43], off
	global_load_dwordx4 v[144:147], v[42:43], off offset:64
	global_load_dwordx4 v[148:151], v[42:43], off offset:512
	global_load_dwordx4 v[152:155], v[42:43], off offset:576
	s_waitcnt vmcnt(3)
	v_pk_fma_f32 v[16:17], v[16:17], v[36:37], v[142:143]
	v_pk_fma_f32 v[14:15], v[14:15], v[34:35], v[140:141]
	v_lshl_add_u64 v[18:19], s[22:23], 0, v[24:25]
	global_store_dwordx4 v[18:19], v[14:17], off
	v_or_b32_e32 v18, v22, v82
	v_mov_b32_e32 v19, v23
	s_waitcnt vmcnt(3)
	v_pk_fma_f32 v[12:13], v[12:13], v[32:33], v[146:147]
	v_pk_fma_f32 v[10:11], v[10:11], v[30:31], v[144:145]
	v_lshl_add_u64 v[14:15], v[18:19], 2, s[22:23]
	global_store_dwordx4 v[14:15], v[10:13], off
	v_or_b32_e32 v14, v22, v83
	v_mov_b32_e32 v15, v23
	v_or_b32_e32 v22, v22, v54
	s_waitcnt vmcnt(3)
	v_pk_fma_f32 v[8:9], v[8:9], v[40:41], v[150:151]
	v_pk_fma_f32 v[6:7], v[6:7], v[38:39], v[148:149]
	v_lshl_add_u64 v[10:11], v[14:15], 2, s[22:23]
	global_store_dwordx4 v[10:11], v[6:9], off
	s_waitcnt vmcnt(3)
	v_pk_fma_f32 v[4:5], v[4:5], v[28:29], v[154:155]
	v_pk_fma_f32 v[2:3], v[2:3], v[26:27], v[152:153]
	v_lshl_add_u64 v[6:7], v[22:23], 2, s[22:23]
	global_store_dwordx4 v[6:7], v[2:5], off
	s_and_b64 vcc, exec, s[0:1]
	s_mov_b32 s52, s49
	s_mov_b64 s[10:11], s[6:7]
	s_mov_b64 s[8:9], s[4:5]
	s_cbranch_vccnz .Lgx_c_exit
	s_cmpk_gt_u32 s40, 0xff
	s_cbranch_scc0 .LBB0_934
	s_barrier
	s_branch .LBB0_934
